# phase H: L2 warm-up touch of the next tile's first k-block (A/B rows) issued at the epilogue start
# speedup vs baseline: 1.0001x; 1.0001x over previous
; DI void phaseH(int wv0, PP p, unsigned char* smem) {
;     ...
;   for (int id = blockIdx.x; id < 128 * 16; id += gridDim.x) {
;     int pm, pn;
;     tile_map_n16(id, pm, pn);
;     const int brow = pm * 256, bcol = pn * 256;
;     const int tid = my_tid(wv0);
;     if (tid < 256) {
;       const float4* s = (const float4*)(SS1 + (size_t)(brow + tid) * 16);
;       const float4 a = s[0], b = s[1], c = s[2], d = s[3];
;       const float t = a.x + a.y + a.z + a.w + b.x + b.y + b.z + b.w + c.x + c.y + c.z + c.w + d.x + d.y + d.z + d.w;
;       sR[tid] = rsqrtf(t * (1.f / 1024.f) + 1e-6f);
;     }
;     f32x4 acc[2][2][4][2];
;     gemm256(wv0, acc, X1B + (size_t)brow * 1024, 1024, (const u16*)(p->ws + OFF_WUPT) + (size_t)bcol * 1024, 1024, 1024, smem);
.LBB0_1133:
	s_load_dword s88, s[16:17], 0x0
	s_waitcnt lgkmcnt(0)
	s_add_i32 s88, s88, s67
	s_cmpk_lt_i32 s88, 0x800
	s_cbranch_scc0 .Lmy_hw_skip
	s_ashr_i32 s83, s88, 4
	s_and_b32 s83, s83, -16
	s_lshl_b32 s84, s88, 1
	s_and_b32 s84, s84, 12
	s_or_b32 s83, s83, s84
	s_bfe_u32 s84, s88, 0x20006
	s_or_b32 s83, s83, s84
	s_lshl_b32 s84, s83, 8
	s_mov_b32 s85, 0
	s_lshl_b64 s[84:85], s[84:85], 11
	s_add_u32 s84, s0, s84
	s_addc_u32 s85, s1, s85
	s_lshl_b32 s86, s88, 3
	s_and_b32 s86, s86, 8
	s_bfe_u32 s87, s88, 0x30003
	s_or_b32 s86, s86, s87
	s_lshl_b32 s86, s86, 19
	s_add_u32 s86, s33, s86
	s_addc_u32 s87, s50, 0
	v_and_b32_e32 v236, 0xff, v142
	v_lshlrev_b32_e32 v236, 11, v236
	v_mov_b32_e32 v238, s84
	v_mov_b32_e32 v239, s85
	v_mov_b32_e32 v240, s86
	v_mov_b32_e32 v241, s87
	v_cmp_gt_u32_e32 vcc, 0x100, v142
	s_nop 1
	v_cndmask_b32_e32 v238, v240, v238, vcc
	v_cndmask_b32_e32 v239, v241, v239, vcc
	v_add_co_u32_e32 v238, vcc, v238, v236
	v_addc_co_u32_e32 v239, vcc, 0, v239, vcc
	global_load_dword v237, v[238:239], off
